# GLA prep: one head per workgroup so its gate weight tables are fetched once
# speedup vs baseline: 1.0024x; 1.0024x over previous
.LBB0_777:
	s_cmp_lt_i32 s90, 8
	s_cselect_b64 s[2:3], -1, 0
	s_add_u32 s36, s88, 0x115d000
	s_addc_u32 s37, s89, 0
	s_and_b64 s[18:19], s[2:3], s[0:1]
	s_andn2_b64 vcc, exec, s[18:19]
	s_cbranch_vccnz .LBB0_852
	s_cmpk_gt_i32 s58, 0x47f
	s_cbranch_scc1 .LBB0_851
	s_waitcnt vmcnt(0)
	v_readfirstlane_b32 s32, v0
	v_and_b32_e32 v2, 63, v0
	s_mov_b32 s33, 0xbfb8aa3b
	s_mov_b32 s35, 0x3f317217
	s_mov_b32 s36, 0x3377d1cf
	s_mov_b32 s37, 0x3d800000
	s_lshr_b32 s32, s32, 6
	v_lshlrev_b32_e32 v3, 3, v2
	v_lshlrev_b32_e32 v2, 2, v2
	s_lshr_b32 s56, s58, 2
	s_mul_hi_u32 s57, s56, 0x71c71c8
	s_mul_i32 s34, s57, 108
	s_add_i32 s34, s34, s56
	s_and_b32 s57, s58, 3
	s_mul_i32 s57, s57, 36
	s_add_i32 s34, s34, s57
	s_mov_b32 s50, 0
	s_mul_hi_u32 s38, s34, 0x1c71c72
	s_mul_i32 s92, s38, 144
	s_sub_i32 s92, s34, s92
	s_mul_hi_u32 s40, s92, 0x71c71c8
	s_mul_i32 s93, s40, 36
	s_sub_i32 s39, s92, s93
	s_lshl_b32 s92, s38, 8
	s_lshl_b32 s93, s39, 6
	s_add_i32 s92, s92, s93
	s_addk_i32 s92, 0x4000
	s_lshl_b32 s94, s38, 11
	s_add_i32 s94, s94, s93
	s_addk_i32 s94, 0xff00
	s_cmp_lt_u32 s39, 4
	s_cselect_b32 s41, s92, s94
	s_lshl_b32 s92, s32, 3
	s_add_i32 s41, s41, s92
	s_lshl_b32 s95, s40, 8
	s_mul_i32 s92, s41, 0x1800
	s_add_u32 s92, s92, s95
	s_add_u32 s42, s96, s92
	s_addc_u32 s43, s97, 0
	s_lshl_b32 s92, s41, 10
	s_add_u32 s92, s92, s95
	s_add_u32 s44, s88, 0xa27d000
	s_addc_u32 s45, s89, 0
	s_add_u32 s44, s44, s92
	s_addc_u32 s45, s45, 0
	s_add_u32 s46, s44, 0x1000000
	s_addc_u32 s47, s45, 0
	s_lshl_b32 s92, s41, 7
	s_add_u32 s48, s88, 0xf1d000
	s_addc_u32 s49, s89, 0
	s_add_u32 s48, s48, s92
	s_addc_u32 s49, s49, 0
	s_lshl_b32 s95, s40, 9
	v_readlane_b32 s52, v251, 18
	v_readlane_b32 s53, v251, 19
	s_nop 3
	s_add_u32 s52, s52, s95
	s_addc_u32 s53, s53, 0
	global_load_dwordx2 v[10:11], v3, s[52:53]
	global_load_dwordx2 v[12:13], v3, s[52:53] offset:2048
	s_add_u32 s52, s52, 0x1000
	s_addc_u32 s53, s53, 0
	global_load_dwordx2 v[14:15], v3, s[52:53]
	global_load_dwordx2 v[16:17], v3, s[52:53] offset:2048
	s_add_u32 s52, s52, 0x1000
	s_addc_u32 s53, s53, 0
	global_load_dwordx2 v[18:19], v3, s[52:53]
	global_load_dwordx2 v[20:21], v3, s[52:53] offset:2048
	s_add_u32 s52, s52, 0x1000
	s_addc_u32 s53, s53, 0
	global_load_dwordx2 v[22:23], v3, s[52:53]
	global_load_dwordx2 v[24:25], v3, s[52:53] offset:2048
	s_add_u32 s52, s52, 0x1000
	s_addc_u32 s53, s53, 0
	global_load_dwordx2 v[26:27], v3, s[52:53]
	global_load_dwordx2 v[28:29], v3, s[52:53] offset:2048
	s_add_u32 s52, s52, 0x1000
	s_addc_u32 s53, s53, 0
	global_load_dwordx2 v[30:31], v3, s[52:53]
	global_load_dwordx2 v[32:33], v3, s[52:53] offset:2048
	s_add_u32 s52, s52, 0x1000
	s_addc_u32 s53, s53, 0
	global_load_dwordx2 v[34:35], v3, s[52:53]
	global_load_dwordx2 v[36:37], v3, s[52:53] offset:2048
	s_add_u32 s52, s52, 0x1000
	s_addc_u32 s53, s53, 0
	global_load_dwordx2 v[38:39], v3, s[52:53]
	global_load_dwordx2 v[40:41], v3, s[52:53] offset:2048
	v_readlane_b32 s52, v251, 24
	v_readlane_b32 s53, v251, 25
	s_nop 3
	s_add_u32 s52, s52, s95
	s_addc_u32 s53, s53, 0
	global_load_dwordx2 v[42:43], v3, s[52:53]
	global_load_dwordx2 v[44:45], v3, s[52:53] offset:2048
	s_add_u32 s52, s52, 0x1000
	s_addc_u32 s53, s53, 0
	global_load_dwordx2 v[46:47], v3, s[52:53]
	global_load_dwordx2 v[48:49], v3, s[52:53] offset:2048
	s_add_u32 s52, s52, 0x1000
	s_addc_u32 s53, s53, 0
	global_load_dwordx2 v[50:51], v3, s[52:53]
	global_load_dwordx2 v[52:53], v3, s[52:53] offset:2048
	s_add_u32 s52, s52, 0x1000
	s_addc_u32 s53, s53, 0
	global_load_dwordx2 v[54:55], v3, s[52:53]
	global_load_dwordx2 v[56:57], v3, s[52:53] offset:2048
	s_add_u32 s52, s52, 0x1000
	s_addc_u32 s53, s53, 0
	global_load_dwordx2 v[58:59], v3, s[52:53]
	global_load_dwordx2 v[60:61], v3, s[52:53] offset:2048
	s_add_u32 s52, s52, 0x1000
	s_addc_u32 s53, s53, 0
	global_load_dwordx2 v[62:63], v3, s[52:53]
	global_load_dwordx2 v[64:65], v3, s[52:53] offset:2048
	s_add_u32 s52, s52, 0x1000
	s_addc_u32 s53, s53, 0
	global_load_dwordx2 v[66:67], v3, s[52:53]
	global_load_dwordx2 v[68:69], v3, s[52:53] offset:2048
	s_add_u32 s52, s52, 0x1000
	s_addc_u32 s53, s53, 0
	global_load_dwordx2 v[70:71], v3, s[52:53]
	global_load_dwordx2 v[72:73], v3, s[52:53] offset:2048
	v_readlane_b32 s52, v251, 20
	v_readlane_b32 s53, v251, 21
	s_nop 3
	s_add_u32 s52, s52, s95
	s_addc_u32 s53, s53, 0
	global_load_dwordx2 v[74:75], v3, s[52:53]
	v_readlane_b32 s52, v251, 26
	v_readlane_b32 s53, v251, 27
	s_nop 3
	s_add_u32 s52, s52, s95
	s_addc_u32 s53, s53, 0
	global_load_dwordx2 v[76:77], v3, s[52:53]
	s_load_dwordx16 s[0:15], s[48:49], 0x0
	s_load_dwordx16 s[64:79], s[48:49], 0x40
	s_mov_b64 s[52:53], s[42:43]
	global_load_dword v200, v2, s[52:53] offset:1024
	s_add_u32 s52, s52, 0x1800
	s_addc_u32 s53, s53, 0
	global_load_dword v201, v2, s[52:53] offset:1024
	s_add_u32 s52, s52, 0x1800
	s_addc_u32 s53, s53, 0
	global_load_dword v202, v2, s[52:53] offset:1024
	s_add_u32 s52, s52, 0x1800
	s_addc_u32 s53, s53, 0
	global_load_dword v203, v2, s[52:53] offset:1024
	s_add_u32 s52, s52, 0x1800
	s_addc_u32 s53, s53, 0
	global_load_dword v204, v2, s[52:53] offset:1024
	s_add_u32 s52, s52, 0x1800
	s_addc_u32 s53, s53, 0
	global_load_dword v205, v2, s[52:53] offset:1024
	s_add_u32 s52, s52, 0x1800
	s_addc_u32 s53, s53, 0
	global_load_dword v206, v2, s[52:53] offset:1024
	s_add_u32 s52, s52, 0x1800
	s_addc_u32 s53, s53, 0
	global_load_dword v207, v2, s[52:53] offset:1024
	s_cmp_lt_u32 s39, 4
	s_cbranch_scc1 .Lp7_noq_load_first
	s_mov_b64 s[52:53], s[42:43]
	global_load_dword v208, v2, s[52:53]
	s_add_u32 s52, s52, 0x1800
	s_addc_u32 s53, s53, 0
	global_load_dword v209, v2, s[52:53]
	s_add_u32 s52, s52, 0x1800
	s_addc_u32 s53, s53, 0
	global_load_dword v210, v2, s[52:53]
	s_add_u32 s52, s52, 0x1800
	s_addc_u32 s53, s53, 0
	global_load_dword v211, v2, s[52:53]
	s_add_u32 s52, s52, 0x1800
	s_addc_u32 s53, s53, 0
	global_load_dword v212, v2, s[52:53]
	s_add_u32 s52, s52, 0x1800
	s_addc_u32 s53, s53, 0
	global_load_dword v213, v2, s[52:53]
	s_add_u32 s52, s52, 0x1800
	s_addc_u32 s53, s53, 0
	global_load_dword v214, v2, s[52:53]
	s_add_u32 s52, s52, 0x1800
	s_addc_u32 s53, s53, 0
	global_load_dword v215, v2, s[52:53]

.Lp7_item:
	v_mov_b32_e32 v80, v200
	v_mov_b32_e32 v81, v201
	v_mov_b32_e32 v82, v202
	v_mov_b32_e32 v83, v203
	v_mov_b32_e32 v84, v204
	v_mov_b32_e32 v85, v205
	v_mov_b32_e32 v86, v206
	v_mov_b32_e32 v87, v207
	v_mov_b32_e32 v88, v208
	v_mov_b32_e32 v89, v209
	v_mov_b32_e32 v90, v210
	v_mov_b32_e32 v91, v211
	v_mov_b32_e32 v92, v212
	v_mov_b32_e32 v93, v213
	v_mov_b32_e32 v94, v214
	v_mov_b32_e32 v95, v215
	s_waitcnt lgkmcnt(0)
	v_pk_fma_f32 v[128:129], v[10:11], s[0:1], v[74:75] op_sel_hi:[1,0,1]
	v_pk_fma_f32 v[128:129], v[12:13], s[0:1], v[128:129] op_sel:[0,1,0] op_sel_hi:[1,1,1]
	v_pk_fma_f32 v[128:129], v[14:15], s[2:3], v[128:129] op_sel_hi:[1,0,1]
	v_pk_fma_f32 v[128:129], v[16:17], s[2:3], v[128:129] op_sel:[0,1,0] op_sel_hi:[1,1,1]
	v_pk_fma_f32 v[128:129], v[18:19], s[4:5], v[128:129] op_sel_hi:[1,0,1]
	v_pk_fma_f32 v[128:129], v[20:21], s[4:5], v[128:129] op_sel:[0,1,0] op_sel_hi:[1,1,1]
	v_pk_fma_f32 v[128:129], v[22:23], s[6:7], v[128:129] op_sel_hi:[1,0,1]
	v_pk_fma_f32 v[128:129], v[24:25], s[6:7], v[128:129] op_sel:[0,1,0] op_sel_hi:[1,1,1]
	v_pk_fma_f32 v[128:129], v[26:27], s[8:9], v[128:129] op_sel_hi:[1,0,1]
	v_pk_fma_f32 v[128:129], v[28:29], s[8:9], v[128:129] op_sel:[0,1,0] op_sel_hi:[1,1,1]
	v_pk_fma_f32 v[128:129], v[30:31], s[10:11], v[128:129] op_sel_hi:[1,0,1]
	v_pk_fma_f32 v[128:129], v[32:33], s[10:11], v[128:129] op_sel:[0,1,0] op_sel_hi:[1,1,1]
	v_pk_fma_f32 v[128:129], v[34:35], s[12:13], v[128:129] op_sel_hi:[1,0,1]
	v_pk_fma_f32 v[128:129], v[36:37], s[12:13], v[128:129] op_sel:[0,1,0] op_sel_hi:[1,1,1]
	v_pk_fma_f32 v[128:129], v[38:39], s[14:15], v[128:129] op_sel_hi:[1,0,1]
	v_pk_fma_f32 v[128:129], v[40:41], s[14:15], v[128:129] op_sel:[0,1,0] op_sel_hi:[1,1,1]
	s_add_u32 s48, s48, 0x80
	s_addc_u32 s49, s49, 0
	s_load_dwordx16 s[0:15], s[48:49], 0x0
	v_pk_fma_f32 v[130:131], v[42:43], s[64:65], v[76:77] op_sel_hi:[1,0,1]
	v_pk_fma_f32 v[130:131], v[44:45], s[64:65], v[130:131] op_sel:[0,1,0] op_sel_hi:[1,1,1]
	v_pk_fma_f32 v[130:131], v[46:47], s[66:67], v[130:131] op_sel_hi:[1,0,1]
	v_pk_fma_f32 v[130:131], v[48:49], s[66:67], v[130:131] op_sel:[0,1,0] op_sel_hi:[1,1,1]
	v_pk_fma_f32 v[130:131], v[50:51], s[68:69], v[130:131] op_sel_hi:[1,0,1]
	v_pk_fma_f32 v[130:131], v[52:53], s[68:69], v[130:131] op_sel:[0,1,0] op_sel_hi:[1,1,1]
	v_pk_fma_f32 v[130:131], v[54:55], s[70:71], v[130:131] op_sel_hi:[1,0,1]
	v_pk_fma_f32 v[130:131], v[56:57], s[70:71], v[130:131] op_sel:[0,1,0] op_sel_hi:[1,1,1]
	v_pk_fma_f32 v[130:131], v[58:59], s[72:73], v[130:131] op_sel_hi:[1,0,1]
	v_pk_fma_f32 v[130:131], v[60:61], s[72:73], v[130:131] op_sel:[0,1,0] op_sel_hi:[1,1,1]
	v_pk_fma_f32 v[130:131], v[62:63], s[74:75], v[130:131] op_sel_hi:[1,0,1]
	v_pk_fma_f32 v[130:131], v[64:65], s[74:75], v[130:131] op_sel:[0,1,0] op_sel_hi:[1,1,1]
	v_pk_fma_f32 v[130:131], v[66:67], s[76:77], v[130:131] op_sel_hi:[1,0,1]
	v_pk_fma_f32 v[130:131], v[68:69], s[76:77], v[130:131] op_sel:[0,1,0] op_sel_hi:[1,1,1]
	v_pk_fma_f32 v[130:131], v[70:71], s[78:79], v[130:131] op_sel_hi:[1,0,1]
	v_pk_fma_f32 v[130:131], v[72:73], s[78:79], v[130:131] op_sel:[0,1,0] op_sel_hi:[1,1,1]
	s_load_dwordx16 s[64:79], s[48:49], 0x40
	v_mul_f32_e64 v132, |v128|, s33
	v_mul_f32_e64 v133, |v129|, s33
	v_mul_f32_e64 v134, |v130|, s33
	v_mul_f32_e64 v135, |v131|, s33
	v_exp_f32_e32 v132, v132
	v_exp_f32_e32 v133, v133
	v_exp_f32_e32 v134, v134
	v_exp_f32_e32 v135, v135
	v_pk_add_f32 v[132:133], v[132:133], 1.0 op_sel_hi:[1,0]
	v_pk_add_f32 v[134:135], v[134:135], 1.0 op_sel_hi:[1,0]
	v_log_f32_e32 v136, v132
	v_log_f32_e32 v137, v133
	v_log_f32_e32 v138, v134
	v_log_f32_e32 v139, v135
	v_pk_mul_f32 v[140:141], v[136:137], s[34:35] op_sel:[0,1] op_sel_hi:[1,1]
	v_pk_mul_f32 v[142:143], v[138:139], s[34:35] op_sel:[0,1] op_sel_hi:[1,1]
	v_pk_fma_f32 v[144:145], v[136:137], s[34:35], v[140:141] op_sel:[0,1,0] op_sel_hi:[1,1,1] neg_lo:[0,0,1] neg_hi:[0,0,1]
	v_pk_fma_f32 v[146:147], v[138:139], s[34:35], v[142:143] op_sel:[0,1,0] op_sel_hi:[1,1,1] neg_lo:[0,0,1] neg_hi:[0,0,1]
	v_pk_fma_f32 v[144:145], v[136:137], s[36:37], v[144:145] op_sel_hi:[1,0,1]
	v_pk_fma_f32 v[146:147], v[138:139], s[36:37], v[146:147] op_sel_hi:[1,0,1]
	v_pk_fma_f32 v[144:145], v[136:137], s[34:35], v[144:145] op_sel:[0,1,0] op_sel_hi:[1,1,1]
	v_pk_fma_f32 v[146:147], v[138:139], s[34:35], v[146:147] op_sel:[0,1,0] op_sel_hi:[1,1,1]
	v_min_f32_e32 v128, 0, v128
	v_min_f32_e32 v129, 0, v129
	v_min_f32_e32 v130, 0, v130
	v_min_f32_e32 v131, 0, v131
	v_pk_add_f32 v[128:129], v[128:129], v[144:145] neg_lo:[0,1] neg_hi:[0,1]
	v_pk_add_f32 v[130:131], v[130:131], v[146:147] neg_lo:[0,1] neg_hi:[0,1]
	v_pk_mul_f32 v[96:97], v[128:129], s[36:37] op_sel:[0,1] op_sel_hi:[1,1]
	v_pk_mul_f32 v[112:113], v[130:131], s[36:37] op_sel:[0,1] op_sel_hi:[1,1]
	s_waitcnt lgkmcnt(0)
	v_pk_fma_f32 v[128:129], v[10:11], s[0:1], v[74:75] op_sel_hi:[1,0,1]
	v_pk_fma_f32 v[128:129], v[12:13], s[0:1], v[128:129] op_sel:[0,1,0] op_sel_hi:[1,1,1]
	v_pk_fma_f32 v[128:129], v[14:15], s[2:3], v[128:129] op_sel_hi:[1,0,1]
	v_pk_fma_f32 v[128:129], v[16:17], s[2:3], v[128:129] op_sel:[0,1,0] op_sel_hi:[1,1,1]
	v_pk_fma_f32 v[128:129], v[18:19], s[4:5], v[128:129] op_sel_hi:[1,0,1]
	v_pk_fma_f32 v[128:129], v[20:21], s[4:5], v[128:129] op_sel:[0,1,0] op_sel_hi:[1,1,1]
	v_pk_fma_f32 v[128:129], v[22:23], s[6:7], v[128:129] op_sel_hi:[1,0,1]
	v_pk_fma_f32 v[128:129], v[24:25], s[6:7], v[128:129] op_sel:[0,1,0] op_sel_hi:[1,1,1]
	v_pk_fma_f32 v[128:129], v[26:27], s[8:9], v[128:129] op_sel_hi:[1,0,1]
	v_pk_fma_f32 v[128:129], v[28:29], s[8:9], v[128:129] op_sel:[0,1,0] op_sel_hi:[1,1,1]
	v_pk_fma_f32 v[128:129], v[30:31], s[10:11], v[128:129] op_sel_hi:[1,0,1]
	v_pk_fma_f32 v[128:129], v[32:33], s[10:11], v[128:129] op_sel:[0,1,0] op_sel_hi:[1,1,1]
	v_pk_fma_f32 v[128:129], v[34:35], s[12:13], v[128:129] op_sel_hi:[1,0,1]
	v_pk_fma_f32 v[128:129], v[36:37], s[12:13], v[128:129] op_sel:[0,1,0] op_sel_hi:[1,1,1]
	v_pk_fma_f32 v[128:129], v[38:39], s[14:15], v[128:129] op_sel_hi:[1,0,1]
	v_pk_fma_f32 v[128:129], v[40:41], s[14:15], v[128:129] op_sel:[0,1,0] op_sel_hi:[1,1,1]
	s_add_u32 s48, s48, 0x80
	s_addc_u32 s49, s49, 0
	s_load_dwordx16 s[0:15], s[48:49], 0x0
	v_pk_fma_f32 v[130:131], v[42:43], s[64:65], v[76:77] op_sel_hi:[1,0,1]
	v_pk_fma_f32 v[130:131], v[44:45], s[64:65], v[130:131] op_sel:[0,1,0] op_sel_hi:[1,1,1]
	v_pk_fma_f32 v[130:131], v[46:47], s[66:67], v[130:131] op_sel_hi:[1,0,1]
	v_pk_fma_f32 v[130:131], v[48:49], s[66:67], v[130:131] op_sel:[0,1,0] op_sel_hi:[1,1,1]
	v_pk_fma_f32 v[130:131], v[50:51], s[68:69], v[130:131] op_sel_hi:[1,0,1]
	v_pk_fma_f32 v[130:131], v[52:53], s[68:69], v[130:131] op_sel:[0,1,0] op_sel_hi:[1,1,1]
	v_pk_fma_f32 v[130:131], v[54:55], s[70:71], v[130:131] op_sel_hi:[1,0,1]
	v_pk_fma_f32 v[130:131], v[56:57], s[70:71], v[130:131] op_sel:[0,1,0] op_sel_hi:[1,1,1]
	v_pk_fma_f32 v[130:131], v[58:59], s[72:73], v[130:131] op_sel_hi:[1,0,1]
	v_pk_fma_f32 v[130:131], v[60:61], s[72:73], v[130:131] op_sel:[0,1,0] op_sel_hi:[1,1,1]
	v_pk_fma_f32 v[130:131], v[62:63], s[74:75], v[130:131] op_sel_hi:[1,0,1]
	v_pk_fma_f32 v[130:131], v[64:65], s[74:75], v[130:131] op_sel:[0,1,0] op_sel_hi:[1,1,1]
	v_pk_fma_f32 v[130:131], v[66:67], s[76:77], v[130:131] op_sel_hi:[1,0,1]
	v_pk_fma_f32 v[130:131], v[68:69], s[76:77], v[130:131] op_sel:[0,1,0] op_sel_hi:[1,1,1]
	v_pk_fma_f32 v[130:131], v[70:71], s[78:79], v[130:131] op_sel_hi:[1,0,1]
	v_pk_fma_f32 v[130:131], v[72:73], s[78:79], v[130:131] op_sel:[0,1,0] op_sel_hi:[1,1,1]
	s_load_dwordx16 s[64:79], s[48:49], 0x40
	v_mul_f32_e64 v132, |v128|, s33
	v_mul_f32_e64 v133, |v129|, s33
	v_mul_f32_e64 v134, |v130|, s33
	v_mul_f32_e64 v135, |v131|, s33
	v_exp_f32_e32 v132, v132
	v_exp_f32_e32 v133, v133
	v_exp_f32_e32 v134, v134
	v_exp_f32_e32 v135, v135
	v_pk_add_f32 v[132:133], v[132:133], 1.0 op_sel_hi:[1,0]
	v_pk_add_f32 v[134:135], v[134:135], 1.0 op_sel_hi:[1,0]
	v_log_f32_e32 v136, v132
	v_log_f32_e32 v137, v133
	v_log_f32_e32 v138, v134
	v_log_f32_e32 v139, v135
	v_pk_mul_f32 v[140:141], v[136:137], s[34:35] op_sel:[0,1] op_sel_hi:[1,1]
	v_pk_mul_f32 v[142:143], v[138:139], s[34:35] op_sel:[0,1] op_sel_hi:[1,1]
	v_pk_fma_f32 v[144:145], v[136:137], s[34:35], v[140:141] op_sel:[0,1,0] op_sel_hi:[1,1,1] neg_lo:[0,0,1] neg_hi:[0,0,1]
	v_pk_fma_f32 v[146:147], v[138:139], s[34:35], v[142:143] op_sel:[0,1,0] op_sel_hi:[1,1,1] neg_lo:[0,0,1] neg_hi:[0,0,1]
	v_pk_fma_f32 v[144:145], v[136:137], s[36:37], v[144:145] op_sel_hi:[1,0,1]
	v_pk_fma_f32 v[146:147], v[138:139], s[36:37], v[146:147] op_sel_hi:[1,0,1]
	v_pk_fma_f32 v[144:145], v[136:137], s[34:35], v[144:145] op_sel:[0,1,0] op_sel_hi:[1,1,1]
	v_pk_fma_f32 v[146:147], v[138:139], s[34:35], v[146:147] op_sel:[0,1,0] op_sel_hi:[1,1,1]
	v_min_f32_e32 v128, 0, v128
	v_min_f32_e32 v129, 0, v129
	v_min_f32_e32 v130, 0, v130
	v_min_f32_e32 v131, 0, v131
	v_pk_add_f32 v[128:129], v[128:129], v[144:145] neg_lo:[0,1] neg_hi:[0,1]
	v_pk_add_f32 v[130:131], v[130:131], v[146:147] neg_lo:[0,1] neg_hi:[0,1]
	v_pk_mul_f32 v[98:99], v[128:129], s[36:37] op_sel:[0,1] op_sel_hi:[1,1]
	v_pk_mul_f32 v[114:115], v[130:131], s[36:37] op_sel:[0,1] op_sel_hi:[1,1]
	s_waitcnt lgkmcnt(0)
	v_pk_fma_f32 v[128:129], v[10:11], s[0:1], v[74:75] op_sel_hi:[1,0,1]
	v_pk_fma_f32 v[128:129], v[12:13], s[0:1], v[128:129] op_sel:[0,1,0] op_sel_hi:[1,1,1]
	v_pk_fma_f32 v[128:129], v[14:15], s[2:3], v[128:129] op_sel_hi:[1,0,1]
	v_pk_fma_f32 v[128:129], v[16:17], s[2:3], v[128:129] op_sel:[0,1,0] op_sel_hi:[1,1,1]
	v_pk_fma_f32 v[128:129], v[18:19], s[4:5], v[128:129] op_sel_hi:[1,0,1]
	v_pk_fma_f32 v[128:129], v[20:21], s[4:5], v[128:129] op_sel:[0,1,0] op_sel_hi:[1,1,1]
	v_pk_fma_f32 v[128:129], v[22:23], s[6:7], v[128:129] op_sel_hi:[1,0,1]
	v_pk_fma_f32 v[128:129], v[24:25], s[6:7], v[128:129] op_sel:[0,1,0] op_sel_hi:[1,1,1]
	v_pk_fma_f32 v[128:129], v[26:27], s[8:9], v[128:129] op_sel_hi:[1,0,1]
	v_pk_fma_f32 v[128:129], v[28:29], s[8:9], v[128:129] op_sel:[0,1,0] op_sel_hi:[1,1,1]
	v_pk_fma_f32 v[128:129], v[30:31], s[10:11], v[128:129] op_sel_hi:[1,0,1]
	v_pk_fma_f32 v[128:129], v[32:33], s[10:11], v[128:129] op_sel:[0,1,0] op_sel_hi:[1,1,1]
	v_pk_fma_f32 v[128:129], v[34:35], s[12:13], v[128:129] op_sel_hi:[1,0,1]
	v_pk_fma_f32 v[128:129], v[36:37], s[12:13], v[128:129] op_sel:[0,1,0] op_sel_hi:[1,1,1]
	v_pk_fma_f32 v[128:129], v[38:39], s[14:15], v[128:129] op_sel_hi:[1,0,1]
	v_pk_fma_f32 v[128:129], v[40:41], s[14:15], v[128:129] op_sel:[0,1,0] op_sel_hi:[1,1,1]
	s_add_u32 s48, s48, 0x80
	s_addc_u32 s49, s49, 0
	s_load_dwordx16 s[0:15], s[48:49], 0x0
	v_pk_fma_f32 v[130:131], v[42:43], s[64:65], v[76:77] op_sel_hi:[1,0,1]
	v_pk_fma_f32 v[130:131], v[44:45], s[64:65], v[130:131] op_sel:[0,1,0] op_sel_hi:[1,1,1]
	v_pk_fma_f32 v[130:131], v[46:47], s[66:67], v[130:131] op_sel_hi:[1,0,1]
	v_pk_fma_f32 v[130:131], v[48:49], s[66:67], v[130:131] op_sel:[0,1,0] op_sel_hi:[1,1,1]
	v_pk_fma_f32 v[130:131], v[50:51], s[68:69], v[130:131] op_sel_hi:[1,0,1]
	v_pk_fma_f32 v[130:131], v[52:53], s[68:69], v[130:131] op_sel:[0,1,0] op_sel_hi:[1,1,1]
	v_pk_fma_f32 v[130:131], v[54:55], s[70:71], v[130:131] op_sel_hi:[1,0,1]
	v_pk_fma_f32 v[130:131], v[56:57], s[70:71], v[130:131] op_sel:[0,1,0] op_sel_hi:[1,1,1]
	v_pk_fma_f32 v[130:131], v[58:59], s[72:73], v[130:131] op_sel_hi:[1,0,1]
	v_pk_fma_f32 v[130:131], v[60:61], s[72:73], v[130:131] op_sel:[0,1,0] op_sel_hi:[1,1,1]
	v_pk_fma_f32 v[130:131], v[62:63], s[74:75], v[130:131] op_sel_hi:[1,0,1]
	v_pk_fma_f32 v[130:131], v[64:65], s[74:75], v[130:131] op_sel:[0,1,0] op_sel_hi:[1,1,1]
	v_pk_fma_f32 v[130:131], v[66:67], s[76:77], v[130:131] op_sel_hi:[1,0,1]
	v_pk_fma_f32 v[130:131], v[68:69], s[76:77], v[130:131] op_sel:[0,1,0] op_sel_hi:[1,1,1]
	v_pk_fma_f32 v[130:131], v[70:71], s[78:79], v[130:131] op_sel_hi:[1,0,1]
	v_pk_fma_f32 v[130:131], v[72:73], s[78:79], v[130:131] op_sel:[0,1,0] op_sel_hi:[1,1,1]
	s_load_dwordx16 s[64:79], s[48:49], 0x40
	v_mul_f32_e64 v132, |v128|, s33
	v_mul_f32_e64 v133, |v129|, s33
	v_mul_f32_e64 v134, |v130|, s33
	v_mul_f32_e64 v135, |v131|, s33
	v_exp_f32_e32 v132, v132
	v_exp_f32_e32 v133, v133
	v_exp_f32_e32 v134, v134
	v_exp_f32_e32 v135, v135
	v_pk_add_f32 v[132:133], v[132:133], 1.0 op_sel_hi:[1,0]
	v_pk_add_f32 v[134:135], v[134:135], 1.0 op_sel_hi:[1,0]
	v_log_f32_e32 v136, v132
	v_log_f32_e32 v137, v133
	v_log_f32_e32 v138, v134
	v_log_f32_e32 v139, v135
	v_pk_mul_f32 v[140:141], v[136:137], s[34:35] op_sel:[0,1] op_sel_hi:[1,1]
	v_pk_mul_f32 v[142:143], v[138:139], s[34:35] op_sel:[0,1] op_sel_hi:[1,1]
	v_pk_fma_f32 v[144:145], v[136:137], s[34:35], v[140:141] op_sel:[0,1,0] op_sel_hi:[1,1,1] neg_lo:[0,0,1] neg_hi:[0,0,1]
	v_pk_fma_f32 v[146:147], v[138:139], s[34:35], v[142:143] op_sel:[0,1,0] op_sel_hi:[1,1,1] neg_lo:[0,0,1] neg_hi:[0,0,1]
	v_pk_fma_f32 v[144:145], v[136:137], s[36:37], v[144:145] op_sel_hi:[1,0,1]
	v_pk_fma_f32 v[146:147], v[138:139], s[36:37], v[146:147] op_sel_hi:[1,0,1]
	v_pk_fma_f32 v[144:145], v[136:137], s[34:35], v[144:145] op_sel:[0,1,0] op_sel_hi:[1,1,1]
	v_pk_fma_f32 v[146:147], v[138:139], s[34:35], v[146:147] op_sel:[0,1,0] op_sel_hi:[1,1,1]
	v_min_f32_e32 v128, 0, v128
	v_min_f32_e32 v129, 0, v129
	v_min_f32_e32 v130, 0, v130
	v_min_f32_e32 v131, 0, v131
	v_pk_add_f32 v[128:129], v[128:129], v[144:145] neg_lo:[0,1] neg_hi:[0,1]
	v_pk_add_f32 v[130:131], v[130:131], v[146:147] neg_lo:[0,1] neg_hi:[0,1]
	v_pk_mul_f32 v[100:101], v[128:129], s[36:37] op_sel:[0,1] op_sel_hi:[1,1]
	v_pk_mul_f32 v[116:117], v[130:131], s[36:37] op_sel:[0,1] op_sel_hi:[1,1]
	s_waitcnt lgkmcnt(0)
	v_pk_fma_f32 v[128:129], v[10:11], s[0:1], v[74:75] op_sel_hi:[1,0,1]
	v_pk_fma_f32 v[128:129], v[12:13], s[0:1], v[128:129] op_sel:[0,1,0] op_sel_hi:[1,1,1]
	v_pk_fma_f32 v[128:129], v[14:15], s[2:3], v[128:129] op_sel_hi:[1,0,1]
	v_pk_fma_f32 v[128:129], v[16:17], s[2:3], v[128:129] op_sel:[0,1,0] op_sel_hi:[1,1,1]
	v_pk_fma_f32 v[128:129], v[18:19], s[4:5], v[128:129] op_sel_hi:[1,0,1]
	v_pk_fma_f32 v[128:129], v[20:21], s[4:5], v[128:129] op_sel:[0,1,0] op_sel_hi:[1,1,1]
	v_pk_fma_f32 v[128:129], v[22:23], s[6:7], v[128:129] op_sel_hi:[1,0,1]
	v_pk_fma_f32 v[128:129], v[24:25], s[6:7], v[128:129] op_sel:[0,1,0] op_sel_hi:[1,1,1]
	v_pk_fma_f32 v[128:129], v[26:27], s[8:9], v[128:129] op_sel_hi:[1,0,1]
	v_pk_fma_f32 v[128:129], v[28:29], s[8:9], v[128:129] op_sel:[0,1,0] op_sel_hi:[1,1,1]
	v_pk_fma_f32 v[128:129], v[30:31], s[10:11], v[128:129] op_sel_hi:[1,0,1]
	v_pk_fma_f32 v[128:129], v[32:33], s[10:11], v[128:129] op_sel:[0,1,0] op_sel_hi:[1,1,1]
	v_pk_fma_f32 v[128:129], v[34:35], s[12:13], v[128:129] op_sel_hi:[1,0,1]
	v_pk_fma_f32 v[128:129], v[36:37], s[12:13], v[128:129] op_sel:[0,1,0] op_sel_hi:[1,1,1]
	v_pk_fma_f32 v[128:129], v[38:39], s[14:15], v[128:129] op_sel_hi:[1,0,1]
	v_pk_fma_f32 v[128:129], v[40:41], s[14:15], v[128:129] op_sel:[0,1,0] op_sel_hi:[1,1,1]
	s_add_u32 s48, s48, 0x80
	s_addc_u32 s49, s49, 0
	s_load_dwordx16 s[0:15], s[48:49], 0x0
	v_pk_fma_f32 v[130:131], v[42:43], s[64:65], v[76:77] op_sel_hi:[1,0,1]
	v_pk_fma_f32 v[130:131], v[44:45], s[64:65], v[130:131] op_sel:[0,1,0] op_sel_hi:[1,1,1]
	v_pk_fma_f32 v[130:131], v[46:47], s[66:67], v[130:131] op_sel_hi:[1,0,1]
	v_pk_fma_f32 v[130:131], v[48:49], s[66:67], v[130:131] op_sel:[0,1,0] op_sel_hi:[1,1,1]
	v_pk_fma_f32 v[130:131], v[50:51], s[68:69], v[130:131] op_sel_hi:[1,0,1]
	v_pk_fma_f32 v[130:131], v[52:53], s[68:69], v[130:131] op_sel:[0,1,0] op_sel_hi:[1,1,1]
	v_pk_fma_f32 v[130:131], v[54:55], s[70:71], v[130:131] op_sel_hi:[1,0,1]
	v_pk_fma_f32 v[130:131], v[56:57], s[70:71], v[130:131] op_sel:[0,1,0] op_sel_hi:[1,1,1]
	v_pk_fma_f32 v[130:131], v[58:59], s[72:73], v[130:131] op_sel_hi:[1,0,1]
	v_pk_fma_f32 v[130:131], v[60:61], s[72:73], v[130:131] op_sel:[0,1,0] op_sel_hi:[1,1,1]
	v_pk_fma_f32 v[130:131], v[62:63], s[74:75], v[130:131] op_sel_hi:[1,0,1]
	v_pk_fma_f32 v[130:131], v[64:65], s[74:75], v[130:131] op_sel:[0,1,0] op_sel_hi:[1,1,1]
	v_pk_fma_f32 v[130:131], v[66:67], s[76:77], v[130:131] op_sel_hi:[1,0,1]
	v_pk_fma_f32 v[130:131], v[68:69], s[76:77], v[130:131] op_sel:[0,1,0] op_sel_hi:[1,1,1]
	v_pk_fma_f32 v[130:131], v[70:71], s[78:79], v[130:131] op_sel_hi:[1,0,1]
	v_pk_fma_f32 v[130:131], v[72:73], s[78:79], v[130:131] op_sel:[0,1,0] op_sel_hi:[1,1,1]
	s_load_dwordx16 s[64:79], s[48:49], 0x40
	v_mul_f32_e64 v132, |v128|, s33
	v_mul_f32_e64 v133, |v129|, s33
	v_mul_f32_e64 v134, |v130|, s33
	v_mul_f32_e64 v135, |v131|, s33
	v_exp_f32_e32 v132, v132
	v_exp_f32_e32 v133, v133
	v_exp_f32_e32 v134, v134
	v_exp_f32_e32 v135, v135
	v_pk_add_f32 v[132:133], v[132:133], 1.0 op_sel_hi:[1,0]
	v_pk_add_f32 v[134:135], v[134:135], 1.0 op_sel_hi:[1,0]
	v_log_f32_e32 v136, v132
	v_log_f32_e32 v137, v133
	v_log_f32_e32 v138, v134
	v_log_f32_e32 v139, v135
	v_pk_mul_f32 v[140:141], v[136:137], s[34:35] op_sel:[0,1] op_sel_hi:[1,1]
	v_pk_mul_f32 v[142:143], v[138:139], s[34:35] op_sel:[0,1] op_sel_hi:[1,1]
	v_pk_fma_f32 v[144:145], v[136:137], s[34:35], v[140:141] op_sel:[0,1,0] op_sel_hi:[1,1,1] neg_lo:[0,0,1] neg_hi:[0,0,1]
	v_pk_fma_f32 v[146:147], v[138:139], s[34:35], v[142:143] op_sel:[0,1,0] op_sel_hi:[1,1,1] neg_lo:[0,0,1] neg_hi:[0,0,1]
	v_pk_fma_f32 v[144:145], v[136:137], s[36:37], v[144:145] op_sel_hi:[1,0,1]
	v_pk_fma_f32 v[146:147], v[138:139], s[36:37], v[146:147] op_sel_hi:[1,0,1]
	v_pk_fma_f32 v[144:145], v[136:137], s[34:35], v[144:145] op_sel:[0,1,0] op_sel_hi:[1,1,1]
	v_pk_fma_f32 v[146:147], v[138:139], s[34:35], v[146:147] op_sel:[0,1,0] op_sel_hi:[1,1,1]
	v_min_f32_e32 v128, 0, v128
	v_min_f32_e32 v129, 0, v129
	v_min_f32_e32 v130, 0, v130
	v_min_f32_e32 v131, 0, v131
	v_pk_add_f32 v[128:129], v[128:129], v[144:145] neg_lo:[0,1] neg_hi:[0,1]
	v_pk_add_f32 v[130:131], v[130:131], v[146:147] neg_lo:[0,1] neg_hi:[0,1]
	v_pk_mul_f32 v[102:103], v[128:129], s[36:37] op_sel:[0,1] op_sel_hi:[1,1]
	v_pk_mul_f32 v[118:119], v[130:131], s[36:37] op_sel:[0,1] op_sel_hi:[1,1]
	s_waitcnt lgkmcnt(0)
	v_pk_fma_f32 v[128:129], v[10:11], s[0:1], v[74:75] op_sel_hi:[1,0,1]
	v_pk_fma_f32 v[128:129], v[12:13], s[0:1], v[128:129] op_sel:[0,1,0] op_sel_hi:[1,1,1]
	v_pk_fma_f32 v[128:129], v[14:15], s[2:3], v[128:129] op_sel_hi:[1,0,1]
	v_pk_fma_f32 v[128:129], v[16:17], s[2:3], v[128:129] op_sel:[0,1,0] op_sel_hi:[1,1,1]
	v_pk_fma_f32 v[128:129], v[18:19], s[4:5], v[128:129] op_sel_hi:[1,0,1]
	v_pk_fma_f32 v[128:129], v[20:21], s[4:5], v[128:129] op_sel:[0,1,0] op_sel_hi:[1,1,1]
	v_pk_fma_f32 v[128:129], v[22:23], s[6:7], v[128:129] op_sel_hi:[1,0,1]
	v_pk_fma_f32 v[128:129], v[24:25], s[6:7], v[128:129] op_sel:[0,1,0] op_sel_hi:[1,1,1]
	v_pk_fma_f32 v[128:129], v[26:27], s[8:9], v[128:129] op_sel_hi:[1,0,1]
	v_pk_fma_f32 v[128:129], v[28:29], s[8:9], v[128:129] op_sel:[0,1,0] op_sel_hi:[1,1,1]
	v_pk_fma_f32 v[128:129], v[30:31], s[10:11], v[128:129] op_sel_hi:[1,0,1]
	v_pk_fma_f32 v[128:129], v[32:33], s[10:11], v[128:129] op_sel:[0,1,0] op_sel_hi:[1,1,1]
	v_pk_fma_f32 v[128:129], v[34:35], s[12:13], v[128:129] op_sel_hi:[1,0,1]
	v_pk_fma_f32 v[128:129], v[36:37], s[12:13], v[128:129] op_sel:[0,1,0] op_sel_hi:[1,1,1]
	v_pk_fma_f32 v[128:129], v[38:39], s[14:15], v[128:129] op_sel_hi:[1,0,1]
	v_pk_fma_f32 v[128:129], v[40:41], s[14:15], v[128:129] op_sel:[0,1,0] op_sel_hi:[1,1,1]
	s_add_u32 s48, s48, 0x80
	s_addc_u32 s49, s49, 0
	s_load_dwordx16 s[0:15], s[48:49], 0x0
	v_pk_fma_f32 v[130:131], v[42:43], s[64:65], v[76:77] op_sel_hi:[1,0,1]
	v_pk_fma_f32 v[130:131], v[44:45], s[64:65], v[130:131] op_sel:[0,1,0] op_sel_hi:[1,1,1]
	v_pk_fma_f32 v[130:131], v[46:47], s[66:67], v[130:131] op_sel_hi:[1,0,1]
	v_pk_fma_f32 v[130:131], v[48:49], s[66:67], v[130:131] op_sel:[0,1,0] op_sel_hi:[1,1,1]
	v_pk_fma_f32 v[130:131], v[50:51], s[68:69], v[130:131] op_sel_hi:[1,0,1]
	v_pk_fma_f32 v[130:131], v[52:53], s[68:69], v[130:131] op_sel:[0,1,0] op_sel_hi:[1,1,1]
	v_pk_fma_f32 v[130:131], v[54:55], s[70:71], v[130:131] op_sel_hi:[1,0,1]
	v_pk_fma_f32 v[130:131], v[56:57], s[70:71], v[130:131] op_sel:[0,1,0] op_sel_hi:[1,1,1]
	v_pk_fma_f32 v[130:131], v[58:59], s[72:73], v[130:131] op_sel_hi:[1,0,1]
	v_pk_fma_f32 v[130:131], v[60:61], s[72:73], v[130:131] op_sel:[0,1,0] op_sel_hi:[1,1,1]
	v_pk_fma_f32 v[130:131], v[62:63], s[74:75], v[130:131] op_sel_hi:[1,0,1]
	v_pk_fma_f32 v[130:131], v[64:65], s[74:75], v[130:131] op_sel:[0,1,0] op_sel_hi:[1,1,1]
	v_pk_fma_f32 v[130:131], v[66:67], s[76:77], v[130:131] op_sel_hi:[1,0,1]
	v_pk_fma_f32 v[130:131], v[68:69], s[76:77], v[130:131] op_sel:[0,1,0] op_sel_hi:[1,1,1]
	v_pk_fma_f32 v[130:131], v[70:71], s[78:79], v[130:131] op_sel_hi:[1,0,1]
	v_pk_fma_f32 v[130:131], v[72:73], s[78:79], v[130:131] op_sel:[0,1,0] op_sel_hi:[1,1,1]
	s_load_dwordx16 s[64:79], s[48:49], 0x40
	v_mul_f32_e64 v132, |v128|, s33
	v_mul_f32_e64 v133, |v129|, s33
	v_mul_f32_e64 v134, |v130|, s33
	v_mul_f32_e64 v135, |v131|, s33
	v_exp_f32_e32 v132, v132
	v_exp_f32_e32 v133, v133
	v_exp_f32_e32 v134, v134
	v_exp_f32_e32 v135, v135
	v_pk_add_f32 v[132:133], v[132:133], 1.0 op_sel_hi:[1,0]
	v_pk_add_f32 v[134:135], v[134:135], 1.0 op_sel_hi:[1,0]
	v_log_f32_e32 v136, v132
	v_log_f32_e32 v137, v133
	v_log_f32_e32 v138, v134
	v_log_f32_e32 v139, v135
	v_pk_mul_f32 v[140:141], v[136:137], s[34:35] op_sel:[0,1] op_sel_hi:[1,1]
	v_pk_mul_f32 v[142:143], v[138:139], s[34:35] op_sel:[0,1] op_sel_hi:[1,1]
	v_pk_fma_f32 v[144:145], v[136:137], s[34:35], v[140:141] op_sel:[0,1,0] op_sel_hi:[1,1,1] neg_lo:[0,0,1] neg_hi:[0,0,1]
	v_pk_fma_f32 v[146:147], v[138:139], s[34:35], v[142:143] op_sel:[0,1,0] op_sel_hi:[1,1,1] neg_lo:[0,0,1] neg_hi:[0,0,1]
	v_pk_fma_f32 v[144:145], v[136:137], s[36:37], v[144:145] op_sel_hi:[1,0,1]
	v_pk_fma_f32 v[146:147], v[138:139], s[36:37], v[146:147] op_sel_hi:[1,0,1]
	v_pk_fma_f32 v[144:145], v[136:137], s[34:35], v[144:145] op_sel:[0,1,0] op_sel_hi:[1,1,1]
	v_pk_fma_f32 v[146:147], v[138:139], s[34:35], v[146:147] op_sel:[0,1,0] op_sel_hi:[1,1,1]
	v_min_f32_e32 v128, 0, v128
	v_min_f32_e32 v129, 0, v129
	v_min_f32_e32 v130, 0, v130
	v_min_f32_e32 v131, 0, v131
	v_pk_add_f32 v[128:129], v[128:129], v[144:145] neg_lo:[0,1] neg_hi:[0,1]
	v_pk_add_f32 v[130:131], v[130:131], v[146:147] neg_lo:[0,1] neg_hi:[0,1]
	v_pk_mul_f32 v[104:105], v[128:129], s[36:37] op_sel:[0,1] op_sel_hi:[1,1]
	v_pk_mul_f32 v[120:121], v[130:131], s[36:37] op_sel:[0,1] op_sel_hi:[1,1]
	s_waitcnt lgkmcnt(0)
	v_pk_fma_f32 v[128:129], v[10:11], s[0:1], v[74:75] op_sel_hi:[1,0,1]
	v_pk_fma_f32 v[128:129], v[12:13], s[0:1], v[128:129] op_sel:[0,1,0] op_sel_hi:[1,1,1]
	v_pk_fma_f32 v[128:129], v[14:15], s[2:3], v[128:129] op_sel_hi:[1,0,1]
	v_pk_fma_f32 v[128:129], v[16:17], s[2:3], v[128:129] op_sel:[0,1,0] op_sel_hi:[1,1,1]
	v_pk_fma_f32 v[128:129], v[18:19], s[4:5], v[128:129] op_sel_hi:[1,0,1]
	v_pk_fma_f32 v[128:129], v[20:21], s[4:5], v[128:129] op_sel:[0,1,0] op_sel_hi:[1,1,1]
	v_pk_fma_f32 v[128:129], v[22:23], s[6:7], v[128:129] op_sel_hi:[1,0,1]
	v_pk_fma_f32 v[128:129], v[24:25], s[6:7], v[128:129] op_sel:[0,1,0] op_sel_hi:[1,1,1]
	v_pk_fma_f32 v[128:129], v[26:27], s[8:9], v[128:129] op_sel_hi:[1,0,1]
	v_pk_fma_f32 v[128:129], v[28:29], s[8:9], v[128:129] op_sel:[0,1,0] op_sel_hi:[1,1,1]
	v_pk_fma_f32 v[128:129], v[30:31], s[10:11], v[128:129] op_sel_hi:[1,0,1]
	v_pk_fma_f32 v[128:129], v[32:33], s[10:11], v[128:129] op_sel:[0,1,0] op_sel_hi:[1,1,1]
	v_pk_fma_f32 v[128:129], v[34:35], s[12:13], v[128:129] op_sel_hi:[1,0,1]
	v_pk_fma_f32 v[128:129], v[36:37], s[12:13], v[128:129] op_sel:[0,1,0] op_sel_hi:[1,1,1]
	v_pk_fma_f32 v[128:129], v[38:39], s[14:15], v[128:129] op_sel_hi:[1,0,1]
	v_pk_fma_f32 v[128:129], v[40:41], s[14:15], v[128:129] op_sel:[0,1,0] op_sel_hi:[1,1,1]
	s_add_u32 s48, s48, 0x80
	s_addc_u32 s49, s49, 0
	s_load_dwordx16 s[0:15], s[48:49], 0x0
	v_pk_fma_f32 v[130:131], v[42:43], s[64:65], v[76:77] op_sel_hi:[1,0,1]
	v_pk_fma_f32 v[130:131], v[44:45], s[64:65], v[130:131] op_sel:[0,1,0] op_sel_hi:[1,1,1]
	v_pk_fma_f32 v[130:131], v[46:47], s[66:67], v[130:131] op_sel_hi:[1,0,1]
	v_pk_fma_f32 v[130:131], v[48:49], s[66:67], v[130:131] op_sel:[0,1,0] op_sel_hi:[1,1,1]
	v_pk_fma_f32 v[130:131], v[50:51], s[68:69], v[130:131] op_sel_hi:[1,0,1]
	v_pk_fma_f32 v[130:131], v[52:53], s[68:69], v[130:131] op_sel:[0,1,0] op_sel_hi:[1,1,1]
	v_pk_fma_f32 v[130:131], v[54:55], s[70:71], v[130:131] op_sel_hi:[1,0,1]
	v_pk_fma_f32 v[130:131], v[56:57], s[70:71], v[130:131] op_sel:[0,1,0] op_sel_hi:[1,1,1]
	v_pk_fma_f32 v[130:131], v[58:59], s[72:73], v[130:131] op_sel_hi:[1,0,1]
	v_pk_fma_f32 v[130:131], v[60:61], s[72:73], v[130:131] op_sel:[0,1,0] op_sel_hi:[1,1,1]
	v_pk_fma_f32 v[130:131], v[62:63], s[74:75], v[130:131] op_sel_hi:[1,0,1]
	v_pk_fma_f32 v[130:131], v[64:65], s[74:75], v[130:131] op_sel:[0,1,0] op_sel_hi:[1,1,1]
	v_pk_fma_f32 v[130:131], v[66:67], s[76:77], v[130:131] op_sel_hi:[1,0,1]
	v_pk_fma_f32 v[130:131], v[68:69], s[76:77], v[130:131] op_sel:[0,1,0] op_sel_hi:[1,1,1]
	v_pk_fma_f32 v[130:131], v[70:71], s[78:79], v[130:131] op_sel_hi:[1,0,1]
	v_pk_fma_f32 v[130:131], v[72:73], s[78:79], v[130:131] op_sel:[0,1,0] op_sel_hi:[1,1,1]
	s_load_dwordx16 s[64:79], s[48:49], 0x40
	v_mul_f32_e64 v132, |v128|, s33
	v_mul_f32_e64 v133, |v129|, s33
	v_mul_f32_e64 v134, |v130|, s33
	v_mul_f32_e64 v135, |v131|, s33
	v_exp_f32_e32 v132, v132
	v_exp_f32_e32 v133, v133
	v_exp_f32_e32 v134, v134
	v_exp_f32_e32 v135, v135
	v_pk_add_f32 v[132:133], v[132:133], 1.0 op_sel_hi:[1,0]
	v_pk_add_f32 v[134:135], v[134:135], 1.0 op_sel_hi:[1,0]
	v_log_f32_e32 v136, v132
	v_log_f32_e32 v137, v133
	v_log_f32_e32 v138, v134
	v_log_f32_e32 v139, v135
	v_pk_mul_f32 v[140:141], v[136:137], s[34:35] op_sel:[0,1] op_sel_hi:[1,1]
	v_pk_mul_f32 v[142:143], v[138:139], s[34:35] op_sel:[0,1] op_sel_hi:[1,1]
	v_pk_fma_f32 v[144:145], v[136:137], s[34:35], v[140:141] op_sel:[0,1,0] op_sel_hi:[1,1,1] neg_lo:[0,0,1] neg_hi:[0,0,1]
	v_pk_fma_f32 v[146:147], v[138:139], s[34:35], v[142:143] op_sel:[0,1,0] op_sel_hi:[1,1,1] neg_lo:[0,0,1] neg_hi:[0,0,1]
	v_pk_fma_f32 v[144:145], v[136:137], s[36:37], v[144:145] op_sel_hi:[1,0,1]
	v_pk_fma_f32 v[146:147], v[138:139], s[36:37], v[146:147] op_sel_hi:[1,0,1]
	v_pk_fma_f32 v[144:145], v[136:137], s[34:35], v[144:145] op_sel:[0,1,0] op_sel_hi:[1,1,1]
	v_pk_fma_f32 v[146:147], v[138:139], s[34:35], v[146:147] op_sel:[0,1,0] op_sel_hi:[1,1,1]
	v_min_f32_e32 v128, 0, v128
	v_min_f32_e32 v129, 0, v129
	v_min_f32_e32 v130, 0, v130
	v_min_f32_e32 v131, 0, v131
	v_pk_add_f32 v[128:129], v[128:129], v[144:145] neg_lo:[0,1] neg_hi:[0,1]
	v_pk_add_f32 v[130:131], v[130:131], v[146:147] neg_lo:[0,1] neg_hi:[0,1]
	v_pk_mul_f32 v[106:107], v[128:129], s[36:37] op_sel:[0,1] op_sel_hi:[1,1]
	v_pk_mul_f32 v[122:123], v[130:131], s[36:37] op_sel:[0,1] op_sel_hi:[1,1]
	s_waitcnt lgkmcnt(0)
	v_pk_fma_f32 v[128:129], v[10:11], s[0:1], v[74:75] op_sel_hi:[1,0,1]
	v_pk_fma_f32 v[128:129], v[12:13], s[0:1], v[128:129] op_sel:[0,1,0] op_sel_hi:[1,1,1]
	v_pk_fma_f32 v[128:129], v[14:15], s[2:3], v[128:129] op_sel_hi:[1,0,1]
	v_pk_fma_f32 v[128:129], v[16:17], s[2:3], v[128:129] op_sel:[0,1,0] op_sel_hi:[1,1,1]
	v_pk_fma_f32 v[128:129], v[18:19], s[4:5], v[128:129] op_sel_hi:[1,0,1]
	v_pk_fma_f32 v[128:129], v[20:21], s[4:5], v[128:129] op_sel:[0,1,0] op_sel_hi:[1,1,1]
	v_pk_fma_f32 v[128:129], v[22:23], s[6:7], v[128:129] op_sel_hi:[1,0,1]
	v_pk_fma_f32 v[128:129], v[24:25], s[6:7], v[128:129] op_sel:[0,1,0] op_sel_hi:[1,1,1]
	v_pk_fma_f32 v[128:129], v[26:27], s[8:9], v[128:129] op_sel_hi:[1,0,1]
	v_pk_fma_f32 v[128:129], v[28:29], s[8:9], v[128:129] op_sel:[0,1,0] op_sel_hi:[1,1,1]
	v_pk_fma_f32 v[128:129], v[30:31], s[10:11], v[128:129] op_sel_hi:[1,0,1]
	v_pk_fma_f32 v[128:129], v[32:33], s[10:11], v[128:129] op_sel:[0,1,0] op_sel_hi:[1,1,1]
	v_pk_fma_f32 v[128:129], v[34:35], s[12:13], v[128:129] op_sel_hi:[1,0,1]
	v_pk_fma_f32 v[128:129], v[36:37], s[12:13], v[128:129] op_sel:[0,1,0] op_sel_hi:[1,1,1]
	v_pk_fma_f32 v[128:129], v[38:39], s[14:15], v[128:129] op_sel_hi:[1,0,1]
	v_pk_fma_f32 v[128:129], v[40:41], s[14:15], v[128:129] op_sel:[0,1,0] op_sel_hi:[1,1,1]
	s_add_u32 s48, s48, 0x80
	s_addc_u32 s49, s49, 0
	s_load_dwordx16 s[0:15], s[48:49], 0x0
	v_pk_fma_f32 v[130:131], v[42:43], s[64:65], v[76:77] op_sel_hi:[1,0,1]
	v_pk_fma_f32 v[130:131], v[44:45], s[64:65], v[130:131] op_sel:[0,1,0] op_sel_hi:[1,1,1]
	v_pk_fma_f32 v[130:131], v[46:47], s[66:67], v[130:131] op_sel_hi:[1,0,1]
	v_pk_fma_f32 v[130:131], v[48:49], s[66:67], v[130:131] op_sel:[0,1,0] op_sel_hi:[1,1,1]
	v_pk_fma_f32 v[130:131], v[50:51], s[68:69], v[130:131] op_sel_hi:[1,0,1]
	v_pk_fma_f32 v[130:131], v[52:53], s[68:69], v[130:131] op_sel:[0,1,0] op_sel_hi:[1,1,1]
	v_pk_fma_f32 v[130:131], v[54:55], s[70:71], v[130:131] op_sel_hi:[1,0,1]
	v_pk_fma_f32 v[130:131], v[56:57], s[70:71], v[130:131] op_sel:[0,1,0] op_sel_hi:[1,1,1]
	v_pk_fma_f32 v[130:131], v[58:59], s[72:73], v[130:131] op_sel_hi:[1,0,1]
	v_pk_fma_f32 v[130:131], v[60:61], s[72:73], v[130:131] op_sel:[0,1,0] op_sel_hi:[1,1,1]
	v_pk_fma_f32 v[130:131], v[62:63], s[74:75], v[130:131] op_sel_hi:[1,0,1]
	v_pk_fma_f32 v[130:131], v[64:65], s[74:75], v[130:131] op_sel:[0,1,0] op_sel_hi:[1,1,1]
	v_pk_fma_f32 v[130:131], v[66:67], s[76:77], v[130:131] op_sel_hi:[1,0,1]
	v_pk_fma_f32 v[130:131], v[68:69], s[76:77], v[130:131] op_sel:[0,1,0] op_sel_hi:[1,1,1]
	v_pk_fma_f32 v[130:131], v[70:71], s[78:79], v[130:131] op_sel_hi:[1,0,1]
	v_pk_fma_f32 v[130:131], v[72:73], s[78:79], v[130:131] op_sel:[0,1,0] op_sel_hi:[1,1,1]
	s_load_dwordx16 s[64:79], s[48:49], 0x40
	v_mul_f32_e64 v132, |v128|, s33
	v_mul_f32_e64 v133, |v129|, s33
	v_mul_f32_e64 v134, |v130|, s33
	v_mul_f32_e64 v135, |v131|, s33
	v_exp_f32_e32 v132, v132
	v_exp_f32_e32 v133, v133
	v_exp_f32_e32 v134, v134
	v_exp_f32_e32 v135, v135
	v_pk_add_f32 v[132:133], v[132:133], 1.0 op_sel_hi:[1,0]
	v_pk_add_f32 v[134:135], v[134:135], 1.0 op_sel_hi:[1,0]
	v_log_f32_e32 v136, v132
	v_log_f32_e32 v137, v133
	v_log_f32_e32 v138, v134
	v_log_f32_e32 v139, v135
	v_pk_mul_f32 v[140:141], v[136:137], s[34:35] op_sel:[0,1] op_sel_hi:[1,1]
	v_pk_mul_f32 v[142:143], v[138:139], s[34:35] op_sel:[0,1] op_sel_hi:[1,1]
	v_pk_fma_f32 v[144:145], v[136:137], s[34:35], v[140:141] op_sel:[0,1,0] op_sel_hi:[1,1,1] neg_lo:[0,0,1] neg_hi:[0,0,1]
	v_pk_fma_f32 v[146:147], v[138:139], s[34:35], v[142:143] op_sel:[0,1,0] op_sel_hi:[1,1,1] neg_lo:[0,0,1] neg_hi:[0,0,1]
	v_pk_fma_f32 v[144:145], v[136:137], s[36:37], v[144:145] op_sel_hi:[1,0,1]
	v_pk_fma_f32 v[146:147], v[138:139], s[36:37], v[146:147] op_sel_hi:[1,0,1]
	v_pk_fma_f32 v[144:145], v[136:137], s[34:35], v[144:145] op_sel:[0,1,0] op_sel_hi:[1,1,1]
	v_pk_fma_f32 v[146:147], v[138:139], s[34:35], v[146:147] op_sel:[0,1,0] op_sel_hi:[1,1,1]
	v_min_f32_e32 v128, 0, v128
	v_min_f32_e32 v129, 0, v129
	v_min_f32_e32 v130, 0, v130
	v_min_f32_e32 v131, 0, v131
	v_pk_add_f32 v[128:129], v[128:129], v[144:145] neg_lo:[0,1] neg_hi:[0,1]
	v_pk_add_f32 v[130:131], v[130:131], v[146:147] neg_lo:[0,1] neg_hi:[0,1]
	v_pk_mul_f32 v[108:109], v[128:129], s[36:37] op_sel:[0,1] op_sel_hi:[1,1]
	v_pk_mul_f32 v[124:125], v[130:131], s[36:37] op_sel:[0,1] op_sel_hi:[1,1]
	s_waitcnt lgkmcnt(0)
	v_pk_fma_f32 v[128:129], v[10:11], s[0:1], v[74:75] op_sel_hi:[1,0,1]
	v_pk_fma_f32 v[128:129], v[12:13], s[0:1], v[128:129] op_sel:[0,1,0] op_sel_hi:[1,1,1]
	v_pk_fma_f32 v[128:129], v[14:15], s[2:3], v[128:129] op_sel_hi:[1,0,1]
	v_pk_fma_f32 v[128:129], v[16:17], s[2:3], v[128:129] op_sel:[0,1,0] op_sel_hi:[1,1,1]
	v_pk_fma_f32 v[128:129], v[18:19], s[4:5], v[128:129] op_sel_hi:[1,0,1]
	v_pk_fma_f32 v[128:129], v[20:21], s[4:5], v[128:129] op_sel:[0,1,0] op_sel_hi:[1,1,1]
	v_pk_fma_f32 v[128:129], v[22:23], s[6:7], v[128:129] op_sel_hi:[1,0,1]
	v_pk_fma_f32 v[128:129], v[24:25], s[6:7], v[128:129] op_sel:[0,1,0] op_sel_hi:[1,1,1]
	v_pk_fma_f32 v[128:129], v[26:27], s[8:9], v[128:129] op_sel_hi:[1,0,1]
	v_pk_fma_f32 v[128:129], v[28:29], s[8:9], v[128:129] op_sel:[0,1,0] op_sel_hi:[1,1,1]
	v_pk_fma_f32 v[128:129], v[30:31], s[10:11], v[128:129] op_sel_hi:[1,0,1]
	v_pk_fma_f32 v[128:129], v[32:33], s[10:11], v[128:129] op_sel:[0,1,0] op_sel_hi:[1,1,1]
	v_pk_fma_f32 v[128:129], v[34:35], s[12:13], v[128:129] op_sel_hi:[1,0,1]
	v_pk_fma_f32 v[128:129], v[36:37], s[12:13], v[128:129] op_sel:[0,1,0] op_sel_hi:[1,1,1]
	v_pk_fma_f32 v[128:129], v[38:39], s[14:15], v[128:129] op_sel_hi:[1,0,1]
	v_pk_fma_f32 v[128:129], v[40:41], s[14:15], v[128:129] op_sel:[0,1,0] op_sel_hi:[1,1,1]
	v_pk_fma_f32 v[130:131], v[42:43], s[64:65], v[76:77] op_sel_hi:[1,0,1]
	v_pk_fma_f32 v[130:131], v[44:45], s[64:65], v[130:131] op_sel:[0,1,0] op_sel_hi:[1,1,1]
	v_pk_fma_f32 v[130:131], v[46:47], s[66:67], v[130:131] op_sel_hi:[1,0,1]
	v_pk_fma_f32 v[130:131], v[48:49], s[66:67], v[130:131] op_sel:[0,1,0] op_sel_hi:[1,1,1]
	v_pk_fma_f32 v[130:131], v[50:51], s[68:69], v[130:131] op_sel_hi:[1,0,1]
	v_pk_fma_f32 v[130:131], v[52:53], s[68:69], v[130:131] op_sel:[0,1,0] op_sel_hi:[1,1,1]
	v_pk_fma_f32 v[130:131], v[54:55], s[70:71], v[130:131] op_sel_hi:[1,0,1]
	v_pk_fma_f32 v[130:131], v[56:57], s[70:71], v[130:131] op_sel:[0,1,0] op_sel_hi:[1,1,1]
	v_pk_fma_f32 v[130:131], v[58:59], s[72:73], v[130:131] op_sel_hi:[1,0,1]
	v_pk_fma_f32 v[130:131], v[60:61], s[72:73], v[130:131] op_sel:[0,1,0] op_sel_hi:[1,1,1]
	v_pk_fma_f32 v[130:131], v[62:63], s[74:75], v[130:131] op_sel_hi:[1,0,1]
	v_pk_fma_f32 v[130:131], v[64:65], s[74:75], v[130:131] op_sel:[0,1,0] op_sel_hi:[1,1,1]
	v_pk_fma_f32 v[130:131], v[66:67], s[76:77], v[130:131] op_sel_hi:[1,0,1]
	v_pk_fma_f32 v[130:131], v[68:69], s[76:77], v[130:131] op_sel:[0,1,0] op_sel_hi:[1,1,1]
	v_pk_fma_f32 v[130:131], v[70:71], s[78:79], v[130:131] op_sel_hi:[1,0,1]
	v_pk_fma_f32 v[130:131], v[72:73], s[78:79], v[130:131] op_sel:[0,1,0] op_sel_hi:[1,1,1]
	v_mul_f32_e64 v132, |v128|, s33
	v_mul_f32_e64 v133, |v129|, s33
	v_mul_f32_e64 v134, |v130|, s33
	v_mul_f32_e64 v135, |v131|, s33
	v_exp_f32_e32 v132, v132
	v_exp_f32_e32 v133, v133
	v_exp_f32_e32 v134, v134
	v_exp_f32_e32 v135, v135
	v_pk_add_f32 v[132:133], v[132:133], 1.0 op_sel_hi:[1,0]
	v_pk_add_f32 v[134:135], v[134:135], 1.0 op_sel_hi:[1,0]
	v_log_f32_e32 v136, v132
	v_log_f32_e32 v137, v133
	v_log_f32_e32 v138, v134
	v_log_f32_e32 v139, v135
	v_pk_mul_f32 v[140:141], v[136:137], s[34:35] op_sel:[0,1] op_sel_hi:[1,1]
	v_pk_mul_f32 v[142:143], v[138:139], s[34:35] op_sel:[0,1] op_sel_hi:[1,1]
	v_pk_fma_f32 v[144:145], v[136:137], s[34:35], v[140:141] op_sel:[0,1,0] op_sel_hi:[1,1,1] neg_lo:[0,0,1] neg_hi:[0,0,1]
	v_pk_fma_f32 v[146:147], v[138:139], s[34:35], v[142:143] op_sel:[0,1,0] op_sel_hi:[1,1,1] neg_lo:[0,0,1] neg_hi:[0,0,1]
	v_pk_fma_f32 v[144:145], v[136:137], s[36:37], v[144:145] op_sel_hi:[1,0,1]
	v_pk_fma_f32 v[146:147], v[138:139], s[36:37], v[146:147] op_sel_hi:[1,0,1]
	v_pk_fma_f32 v[144:145], v[136:137], s[34:35], v[144:145] op_sel:[0,1,0] op_sel_hi:[1,1,1]
	v_pk_fma_f32 v[146:147], v[138:139], s[34:35], v[146:147] op_sel:[0,1,0] op_sel_hi:[1,1,1]
	v_min_f32_e32 v128, 0, v128
	v_min_f32_e32 v129, 0, v129
	v_min_f32_e32 v130, 0, v130
	v_min_f32_e32 v131, 0, v131
	v_pk_add_f32 v[128:129], v[128:129], v[144:145] neg_lo:[0,1] neg_hi:[0,1]
	v_pk_add_f32 v[130:131], v[130:131], v[146:147] neg_lo:[0,1] neg_hi:[0,1]
	v_pk_mul_f32 v[110:111], v[128:129], s[36:37] op_sel:[0,1] op_sel_hi:[1,1]
	v_pk_mul_f32 v[126:127], v[130:131], s[36:37] op_sel:[0,1] op_sel_hi:[1,1]
	v_readlane_b32 s69, v251, 49
	s_nop 3
	s_add_i32 s56, s56, 64
	s_movk_i32 s51, 0x480
	s_cmpk_lt_i32 s56, 0x120
	s_cbranch_scc0 .Lp7_jdone
	s_mul_hi_u32 s57, s56, 0x71c71c8
	s_mul_i32 s51, s57, 108
	s_add_i32 s51, s51, s56
	s_and_b32 s57, s58, 3
	s_mul_i32 s57, s57, 36
	s_add_i32 s51, s51, s57
.Lp7_jdone:
	s_cmpk_lt_i32 s51, 0x480
	s_cbranch_scc0 .Lp7_no_prefetch
	s_mul_hi_u32 s80, s51, 0x1c71c72
	s_mul_i32 s92, s80, 144
	s_sub_i32 s92, s51, s92
	s_mul_hi_u32 s82, s92, 0x71c71c8
	s_mul_i32 s93, s82, 36
	s_sub_i32 s81, s92, s93
	s_lshl_b32 s92, s80, 8
	s_lshl_b32 s93, s81, 6
	s_add_i32 s92, s92, s93
	s_addk_i32 s92, 0x4000
	s_lshl_b32 s94, s80, 11
	s_add_i32 s94, s94, s93
	s_addk_i32 s94, 0xff00
	s_cmp_lt_u32 s81, 4
	s_cselect_b32 s83, s92, s94
	s_lshl_b32 s92, s32, 3
	s_add_i32 s83, s83, s92
	s_lshl_b32 s95, s82, 8
	s_mul_i32 s92, s83, 0x1800
	s_add_u32 s92, s92, s95
	s_add_u32 s84, s96, s92
	s_addc_u32 s85, s97, 0
	s_lshl_b32 s92, s83, 10
	s_add_u32 s92, s92, s95
	s_add_u32 s86, s88, 0xa27d000
	s_addc_u32 s87, s89, 0
	s_add_u32 s86, s86, s92
	s_addc_u32 s87, s87, 0
	s_add_u32 s98, s86, 0x1000000
	s_addc_u32 s99, s87, 0
	s_lshl_b32 s92, s83, 7
	s_add_u32 s100, s88, 0xf1d000
	s_addc_u32 s101, s89, 0
	s_add_u32 s100, s100, s92
	s_addc_u32 s101, s101, 0
	s_lshl_b32 s95, s82, 9
	s_load_dwordx16 s[0:15], s[100:101], 0x0
	s_load_dwordx16 s[64:79], s[100:101], 0x40
	s_mov_b64 s[52:53], s[84:85]
	global_load_dword v200, v2, s[52:53] offset:1024
	s_add_u32 s52, s52, 0x1800
	s_addc_u32 s53, s53, 0
	global_load_dword v201, v2, s[52:53] offset:1024
	s_add_u32 s52, s52, 0x1800
	s_addc_u32 s53, s53, 0
	global_load_dword v202, v2, s[52:53] offset:1024
	s_add_u32 s52, s52, 0x1800
	s_addc_u32 s53, s53, 0
	global_load_dword v203, v2, s[52:53] offset:1024
	s_add_u32 s52, s52, 0x1800
	s_addc_u32 s53, s53, 0
	global_load_dword v204, v2, s[52:53] offset:1024
	s_add_u32 s52, s52, 0x1800
	s_addc_u32 s53, s53, 0
	global_load_dword v205, v2, s[52:53] offset:1024
	s_add_u32 s52, s52, 0x1800
	s_addc_u32 s53, s53, 0
	global_load_dword v206, v2, s[52:53] offset:1024
	s_add_u32 s52, s52, 0x1800
	s_addc_u32 s53, s53, 0
	global_load_dword v207, v2, s[52:53] offset:1024
	s_cmp_lt_u32 s81, 4
	s_cbranch_scc1 .Lp7_noq_load_next
	s_mov_b64 s[52:53], s[84:85]
	global_load_dword v208, v2, s[52:53]
	s_add_u32 s52, s52, 0x1800
	s_addc_u32 s53, s53, 0
	global_load_dword v209, v2, s[52:53]
	s_add_u32 s52, s52, 0x1800
	s_addc_u32 s53, s53, 0
	global_load_dword v210, v2, s[52:53]
	s_add_u32 s52, s52, 0x1800
	s_addc_u32 s53, s53, 0
	global_load_dword v211, v2, s[52:53]
	s_add_u32 s52, s52, 0x1800
	s_addc_u32 s53, s53, 0
	global_load_dword v212, v2, s[52:53]
	s_add_u32 s52, s52, 0x1800
	s_addc_u32 s53, s53, 0
	global_load_dword v213, v2, s[52:53]
	s_add_u32 s52, s52, 0x1800
	s_addc_u32 s53, s53, 0
	global_load_dword v214, v2, s[52:53]
	s_add_u32 s52, s52, 0x1800
	s_addc_u32 s53, s53, 0
	global_load_dword v215, v2, s[52:53]
